# attention item-0 K/V tiles: use the pre-barrier LDS-DMA (retargeted to ring layout) instead of reloading
# speedup vs baseline: 1.0036x; 1.0036x over previous
.LBB0_680:
	v_readlane_b32 s0, v254, 48
	v_readlane_b32 s1, v254, 49
	s_xor_b64 s[0:1], s[0:1], -1
	v_writelane_b32 v254, s0, 56
	s_andn2_b64 vcc, exec, s[0:1]
	s_nop 0
	v_writelane_b32 v254, s1, 57
	s_cbranch_vccnz .LBB0_682
	v_mov_b32_e32 v0, v170
	v_readlane_b32 s6, v253, 30
	v_readfirstlane_b32 s0, v0
	v_and_b32_e32 v4, 63, v0
	s_ashr_i32 s0, s0, 6
	v_mov_b32_e32 v5, v4
	s_lshl_b32 s1, s0, 3
	v_ashrrev_i32_e32 v6, 3, v5
	v_add_u32_e32 v0, s1, v6
	v_lshrrev_b32_e32 v1, 1, v0
	v_xor_b32_e32 v2, v1, v5
	v_ashrrev_i32_e32 v1, 31, v0
	v_lshlrev_b64 v[0:1], 7, v[0:1]
	v_readlane_b32 s7, v253, 31
	v_lshlrev_b32_e32 v2, 4, v2
	v_and_b32_e32 v2, 0x70, v2
	v_lshl_add_u64 v[0:1], s[6:7], 0, v[0:1]
	s_lshl_b32 s2, s0, 10
	s_add_i32 s3, 0, 0x18000
	s_add_i32 s4, s0, 8
	v_lshl_add_u64 v[0:1], v[0:1], 0, v[2:3]
	s_add_i32 m0, s3, s2
	s_bitset0_b32 m0, 16
	s_bitset1_b32 m0, 14
	s_lshl_b32 s5, s4, 3
	global_load_lds_dwordx4 v[0:1], off
	v_add_u32_e32 v0, s5, v6
	v_lshrrev_b32_e32 v1, 1, v0
	v_xor_b32_e32 v2, v1, v5
	v_ashrrev_i32_e32 v1, 31, v0
	v_lshlrev_b64 v[0:1], 7, v[0:1]
	v_lshlrev_b32_e32 v2, 4, v2
	v_lshl_add_u64 v[0:1], s[6:7], 0, v[0:1]
	v_and_b32_e32 v2, 0x70, v2
	s_lshl_b32 s6, s4, 10
	v_lshl_add_u64 v[0:1], v[0:1], 0, v[2:3]
	s_add_i32 m0, s3, s6
	s_bitset0_b32 m0, 16
	s_bitset1_b32 m0, 14
	v_ashrrev_i32_e32 v6, 4, v5
	s_lshl_b32 s0, s0, 2
	global_load_lds_dwordx4 v[0:1], off
	v_add_u32_e32 v0, s0, v6
	v_xor_b32_e32 v2, v0, v5
	v_ashrrev_i32_e32 v1, 31, v0
	v_readlane_b32 s8, v253, 32
	v_lshlrev_b64 v[0:1], 15, v[0:1]
	v_readlane_b32 s9, v253, 33
	v_lshlrev_b32_e32 v2, 4, v2
	v_and_b32_e32 v2, 0xf0, v2
	v_lshl_add_u64 v[0:1], s[8:9], 0, v[0:1]
	s_add_i32 s3, 0, 0x1c000
	v_lshl_add_u64 v[0:1], v[0:1], 0, v[2:3]
	s_add_i32 m0, s3, s2
	s_lshl_b32 s4, s4, 2
	global_load_lds_dwordx4 v[0:1], off
	v_add_u32_e32 v0, s4, v6
	v_xor_b32_e32 v2, v0, v5
	v_ashrrev_i32_e32 v1, 31, v0
	v_lshlrev_b64 v[0:1], 15, v[0:1]
	v_lshlrev_b32_e32 v2, 4, v2
	v_lshl_add_u64 v[0:1], s[8:9], 0, v[0:1]
	v_and_b32_e32 v2, 0xf0, v2
	v_lshl_add_u64 v[0:1], v[0:1], 0, v[2:3]
	s_add_i32 m0, s3, s6
	v_readlane_b32 s8, v253, 34
	global_load_lds_dwordx4 v[0:1], off
	v_readlane_b32 s9, v253, 35
	v_ashrrev_i32_e32 v5, 3, v4
	v_add_u32_e32 v0, s1, v5
	v_lshrrev_b32_e32 v1, 1, v0
	v_xor_b32_e32 v2, v1, v4
	v_ashrrev_i32_e32 v1, 31, v0
	v_lshlrev_b64 v[0:1], 7, v[0:1]
	v_lshlrev_b32_e32 v2, 4, v2
	v_lshl_add_u64 v[0:1], s[8:9], 0, v[0:1]
	v_and_b32_e32 v2, 0x70, v2
	s_add_i32 s1, s2, 0
	v_lshl_add_u64 v[0:1], v[0:1], 0, v[2:3]
	s_mov_b32 m0, s1
	s_add_i32 s2, s6, 0
	global_load_lds_dwordx4 v[0:1], off
	v_add_u32_e32 v0, s5, v5
	v_lshrrev_b32_e32 v1, 1, v0
	v_xor_b32_e32 v2, v1, v4
	v_ashrrev_i32_e32 v1, 31, v0
	v_lshlrev_b64 v[0:1], 7, v[0:1]
	v_lshlrev_b32_e32 v2, 4, v2
	v_lshl_add_u64 v[0:1], s[8:9], 0, v[0:1]
	v_and_b32_e32 v2, 0x70, v2
	v_lshl_add_u64 v[0:1], v[0:1], 0, v[2:3]
	s_mov_b32 m0, s2
	v_ashrrev_i32_e32 v5, 4, v4
	global_load_lds_dwordx4 v[0:1], off
	v_add_u32_e32 v0, s0, v5
	v_xor_b32_e32 v2, v0, v4
	v_ashrrev_i32_e32 v1, 31, v0
	v_readlane_b32 s6, v253, 37
	v_lshlrev_b64 v[0:1], 15, v[0:1]
	v_readlane_b32 s7, v253, 38
	v_lshlrev_b32_e32 v2, 4, v2
	v_and_b32_e32 v2, 0xf0, v2
	v_lshl_add_u64 v[0:1], s[6:7], 0, v[0:1]
	v_lshl_add_u64 v[0:1], v[0:1], 0, v[2:3]
	s_add_i32 m0, s1, 0x4000
	s_bitset0_b32 m0, 14
	s_bitset1_b32 m0, 16
	s_nop 0
	global_load_lds_dwordx4 v[0:1], off
	v_add_u32_e32 v0, s4, v5
	v_xor_b32_e32 v2, v0, v4
	v_ashrrev_i32_e32 v1, 31, v0
	v_lshlrev_b64 v[0:1], 15, v[0:1]
	v_lshlrev_b32_e32 v2, 4, v2
	v_lshl_add_u64 v[0:1], s[6:7], 0, v[0:1]
	v_and_b32_e32 v2, 0xf0, v2
	v_lshl_add_u64 v[0:1], v[0:1], 0, v[2:3]
	s_add_i32 m0, s2, 0x4000
	s_bitset0_b32 m0, 14
	s_bitset1_b32 m0, 16
	s_nop 0
	global_load_lds_dwordx4 v[0:1], off

.LBB0_738:
	s_waitcnt vmcnt(0) lgkmcnt(0)
	s_mov_b32 s79, 0x3e38aa3b
	s_mov_b32 s77, 0xc000
	s_mov_b32 s78, 0xffffc000
	v_readlane_b32 s1, v253, 23
	v_readfirstlane_b32 s0, v170
	s_nop 3
	s_lshr_b32 s0, s0, 6
	s_and_b32 s74, s1, 7
	s_lshl_b32 s74, s74, 5
	s_lshr_b32 s75, s1, 3
	s_add_u32 s74, s74, s75
	s_lshl_b32 s74, s74, 3
	s_and_b32 s4, s74, 31
	s_lshr_b32 s75, s74, 5
	s_and_b32 s5, s75, 0
	s_lshr_b32 s75, s75, 0
	s_and_b32 s3, s75, 3
	s_lshr_b32 s2, s75, 2
	s_sub_u32 s6, 8, s0
	s_lshl_b32 s70, s0, 10
	s_lshl_b32 s74, s2, 21
	s_lshl_b32 s75, s3, 19
	s_add_u32 s74, s74, s75
	s_add_u32 s34, s40, s74
	s_addc_u32 s35, s41, 0
	s_mov_b32 s30, s34
	s_mov_b32 s31, s35
	s_lshl_b32 s74, s2, 16
	s_lshl_b32 s75, s3, 14
	s_add_u32 s74, s74, s75
	s_add_u32 s74, s74, 0xc000000
	s_add_u32 s58, s42, s74
	s_addc_u32 s59, s43, 0
	s_add_u32 s74, s2, 0
	s_lshl_b32 s74, s74, 2
	s_add_u32 s74, s74, s3
	s_lshl_b32 s74, s74, 19
	s_add_u32 s60, s42, s74
	s_addc_u32 s61, s43, 0
	s_lshl_b32 s74, s2, 6
	s_add_u32 s74, s74, 0
	s_lshl_b32 s74, s74, 15
	s_lshl_b32 s75, s3, 13
	s_add_u32 s74, s74, s75
	s_add_u32 s74, s74, 0x6000000
	s_add_u32 s64, s42, s74
	s_addc_u32 s65, s43, 0
	v_and_b32_e32 v141, 63, v170
	v_and_b32_e32 v241, 15, v141
	v_lshrrev_b32_e32 v242, 4, v141
	v_mov_b32_e32 v244, 0xf149f2ca
	v_mov_b32_e32 v248, 0
	v_mov_b32_e32 v249, 0
	v_lshrrev_b32_e32 v142, 1, v241
	v_xor_b32_e32 v142, v142, v242
	v_lshlrev_b32_e32 v142, 4, v142
	v_lshl_add_u32 v142, v241, 7, v142
	s_lshl_b32 s74, s0, 11
	v_add_u32_e32 v230, s74, v142
	v_xor_b32_e32 v231, 64, v230
	v_lshrrev_b32_e32 v142, 1, v242
	v_xor_b32_e32 v243, v142, v241
	v_and_b32_e32 v142, 1, v242
	v_lshlrev_b32_e32 v142, 3, v142
	v_lshl_add_u32 v142, v241, 8, v142
	v_add_u32_e32 v142, 0x10000, v142
	s_add_u32 s74, s0, 0
	s_and_b32 s75, s74, 7
	s_lshl_b32 s75, s75, 1
	s_lshr_b32 s74, s74, 3
	s_lshl_b32 s74, s74, 14
	v_xor_b32_e32 v143, s75, v243
	v_lshl_add_u32 v143, v143, 4, v142
	v_add_u32_e32 v221, s74, v143
	s_add_u32 s74, s0, 1
	s_and_b32 s75, s74, 7
	s_lshl_b32 s75, s75, 1
	s_lshr_b32 s74, s74, 3
	s_lshl_b32 s74, s74, 14
	v_xor_b32_e32 v143, s75, v243
	v_lshl_add_u32 v143, v143, 4, v142
	v_add_u32_e32 v222, s74, v143
	s_add_u32 s74, s0, 2
	s_and_b32 s75, s74, 7
	s_lshl_b32 s75, s75, 1
	s_lshr_b32 s74, s74, 3
	s_lshl_b32 s74, s74, 14
	v_xor_b32_e32 v143, s75, v243
	v_lshl_add_u32 v143, v143, 4, v142
	v_add_u32_e32 v223, s74, v143
	s_add_u32 s74, s0, 3
	s_and_b32 s75, s74, 7
	s_lshl_b32 s75, s75, 1
	s_lshr_b32 s74, s74, 3
	s_lshl_b32 s74, s74, 14
	v_xor_b32_e32 v143, s75, v243
	v_lshl_add_u32 v143, v143, 4, v142
	v_add_u32_e32 v224, s74, v143
	s_add_u32 s74, s0, 4
	s_and_b32 s75, s74, 7
	s_lshl_b32 s75, s75, 1
	s_lshr_b32 s74, s74, 3
	s_lshl_b32 s74, s74, 14
	v_xor_b32_e32 v143, s75, v243
	v_lshl_add_u32 v143, v143, 4, v142
	v_add_u32_e32 v225, s74, v143
	s_add_u32 s74, s0, 5
	s_and_b32 s75, s74, 7
	s_lshl_b32 s75, s75, 1
	s_lshr_b32 s74, s74, 3
	s_lshl_b32 s74, s74, 14
	v_xor_b32_e32 v143, s75, v243
	v_lshl_add_u32 v143, v143, 4, v142
	v_add_u32_e32 v226, s74, v143
	s_add_u32 s74, s0, 6
	s_and_b32 s75, s74, 7
	s_lshl_b32 s75, s75, 1
	s_lshr_b32 s74, s74, 3
	s_lshl_b32 s74, s74, 14
	v_xor_b32_e32 v143, s75, v243
	v_lshl_add_u32 v143, v143, 4, v142
	v_add_u32_e32 v227, s74, v143
	s_add_u32 s74, s0, 7
	s_and_b32 s75, s74, 7
	s_lshl_b32 s75, s75, 1
	s_lshr_b32 s74, s74, 3
	s_lshl_b32 s74, s74, 14
	v_xor_b32_e32 v143, s75, v243
	v_lshl_add_u32 v143, v143, 4, v142
	v_add_u32_e32 v228, s74, v143
	s_add_u32 s74, s0, 8
	s_and_b32 s75, s74, 7
	s_lshl_b32 s75, s75, 1
	s_lshr_b32 s74, s74, 3
	s_lshl_b32 s74, s74, 14
	v_xor_b32_e32 v143, s75, v243
	v_lshl_add_u32 v143, v143, 4, v142
	v_add_u32_e32 v229, s74, v143
	s_and_b32 s74, s0, 1
	s_lshl_b32 s74, s74, 2
	v_add_u32_e32 v142, s74, v242
	v_and_b32_e32 v143, 7, v141
	v_xor_b32_e32 v142, v142, v143
	v_lshlrev_b32_e32 v142, 4, v142
	v_lshrrev_b32_e32 v143, 3, v141
	s_lshl_b32 s74, s0, 3
	v_add_u32_e32 v143, s74, v143
	v_lshl_add_u32 v232, v143, 7, v142
	v_add_u32_e32 v233, 0x2000, v232
	s_and_b32 s74, s0, 3
	s_lshl_b32 s74, s74, 2
	v_add_u32_e32 v142, s74, v242
	v_xor_b32_e32 v142, v142, v241
	v_lshlrev_b32_e32 v142, 4, v142
	s_lshl_b32 s74, s0, 2
	v_add_u32_e32 v143, s74, v242
	v_lshl_add_u32 v234, v143, 15, v142
	v_add_u32_e32 v235, 0x100000, v234
	s_lshl_b32 s74, s0, 4
	v_add_u32_e32 v142, s74, v241
	v_lshlrev_b32_e32 v142, 0, v142
	v_lshlrev_b32_e32 v238, 2, v142
	v_lshlrev_b32_e32 v142, 7, v142
	v_lshl_add_u32 v236, v242, 4, v142
	v_lshl_add_u32 v237, v242, 3, v142
	v_xor_b32_e32 v142, 16, v141
	v_lshlrev_b32_e32 v239, 2, v142
	v_xor_b32_e32 v142, 32, v141
	v_lshlrev_b32_e32 v240, 2, v142
	s_add_u32 s74, s2, 1
	v_cvt_f32_u32_e32 v142, s74
	v_mul_f32_e32 v142, 0xc1000000, v142
	v_mul_f32_e32 v142, 0x3caaaaab, v142
	v_exp_f32_e32 v142, v142
	v_lshlrev_b32_e32 v144, 2, v242
	v_sub_u32_e32 v145, v241, v144
	v_mul_f32_e32 v142, 0x3f800000, v142
	v_add_u32_e32 v145, 0x80, v145
	v_mul_f32_e32 v142, 0x3fb8aa3b, v142
	v_cvt_f32_i32_e32 v145, v145
	s_nop 0
	v_mul_f32_e64 v143, -v142, v145
	v_fmamk_f32 v185, v142, 0x0, v143
	v_fmamk_f32 v186, v142, 0x3f800000, v143
	v_fmamk_f32 v187, v142, 0x40000000, v143
	v_fmamk_f32 v188, v142, 0x40400000, v143
	v_fmamk_f32 v189, v142, 0x41800000, v143
	v_fmamk_f32 v190, v142, 0x41880000, v143
	v_fmamk_f32 v191, v142, 0x41900000, v143
	v_fmamk_f32 v192, v142, 0x41980000, v143
	v_fmamk_f32 v193, v142, 0x42000000, v143
	v_fmamk_f32 v194, v142, 0x42040000, v143
	v_fmamk_f32 v195, v142, 0x42080000, v143
	v_fmamk_f32 v196, v142, 0x420c0000, v143
	v_fmamk_f32 v197, v142, 0x42400000, v143
	v_fmamk_f32 v198, v142, 0x42440000, v143
	v_fmamk_f32 v199, v142, 0x42480000, v143
	v_fmamk_f32 v200, v142, 0x424c0000, v143
	v_fmamk_f32 v201, v142, 0x42800000, v143
	v_fmamk_f32 v202, v142, 0x42820000, v143
	v_fmamk_f32 v203, v142, 0x42840000, v143
	v_fmamk_f32 v204, v142, 0x42860000, v143
	v_fmamk_f32 v205, v142, 0x42a00000, v143
	v_fmamk_f32 v206, v142, 0x42a20000, v143
	v_fmamk_f32 v207, v142, 0x42a40000, v143
	v_fmamk_f32 v208, v142, 0x42a60000, v143
	v_fmamk_f32 v209, v142, 0x42c00000, v143
	v_fmamk_f32 v210, v142, 0x42c20000, v143
	v_fmamk_f32 v211, v142, 0x42c40000, v143
	v_fmamk_f32 v212, v142, 0x42c60000, v143
	v_fmamk_f32 v213, v142, 0x42e00000, v143
	v_fmamk_f32 v214, v142, 0x42e20000, v143
	v_fmamk_f32 v215, v142, 0x42e40000, v143
	v_fmamk_f32 v216, v142, 0x42e60000, v143
	v_fmamk_f32 v217, v142, 0x43000000, v143
	v_fmamk_f32 v218, v142, 0x43010000, v143
	v_fmamk_f32 v219, v142, 0x43020000, v143
	v_fmamk_f32 v220, v142, 0x43030000, v143
	v_add_u32_e32 v145, 0, v144
	v_cmp_lt_u32_e32 vcc, v145, v241
	s_nop 1
	v_cndmask_b32_e32 v185, v185, v244, vcc
	v_cmp_gt_u32_e32 vcc, v145, v241
	s_nop 1
	v_cndmask_b32_e32 v217, v217, v244, vcc
	v_add_u32_e32 v145, 1, v144
	v_cmp_lt_u32_e32 vcc, v145, v241
	s_nop 1
	v_cndmask_b32_e32 v186, v186, v244, vcc
	v_cmp_gt_u32_e32 vcc, v145, v241
	s_nop 1
	v_cndmask_b32_e32 v218, v218, v244, vcc
	v_add_u32_e32 v145, 2, v144
	v_cmp_lt_u32_e32 vcc, v145, v241
	s_nop 1
	v_cndmask_b32_e32 v187, v187, v244, vcc
	v_cmp_gt_u32_e32 vcc, v145, v241
	s_nop 1
	v_cndmask_b32_e32 v219, v219, v244, vcc
	v_add_u32_e32 v145, 3, v144
	v_cmp_lt_u32_e32 vcc, v145, v241
	s_nop 1
	v_cndmask_b32_e32 v188, v188, v244, vcc
	v_cmp_gt_u32_e32 vcc, v145, v241
	s_nop 1
	v_cndmask_b32_e32 v220, v220, v244, vcc
	s_lshl_b32 s74, s4, 7
	s_add_u32 s74, s74, s5
	s_lshl_b32 s75, s74, 7
	s_add_u32 s10, s30, s75
	s_addc_u32 s11, s31, 0
	s_add_u32 s86, s34, s75
	s_addc_u32 s87, s35, 0
	s_lshl_b32 s75, s74, 2
	s_add_u32 s88, s58, s75
	s_addc_u32 s89, s59, 0
	global_load_dwordx4 v[96:99], v236, s[10:11]
	global_load_dwordx4 v[100:103], v236, s[10:11] offset:64
	s_mov_b32 s7, 0

.LBB0_765:
	v_mov_b32_e32 v0, v170
	v_readlane_b32 s6, v253, 49
	v_readfirstlane_b32 s0, v0
	v_and_b32_e32 v63, 63, v0
	s_ashr_i32 s2, s0, 6
	v_mov_b32_e32 v1, v63
	s_lshl_b32 s0, s2, 3
	s_waitcnt vmcnt(2)
	v_ashrrev_i32_e32 v6, 3, v1
	v_add_u32_e32 v4, s0, v6
	v_lshrrev_b32_e32 v2, 1, v4
	v_xor_b32_e32 v2, v2, v1
	v_ashrrev_i32_e32 v5, 31, v4
	v_lshlrev_b64 v[4:5], 7, v[4:5]
	v_readlane_b32 s7, v253, 50
	v_lshlrev_b32_e32 v2, 4, v2
	s_lshl_b32 s35, s2, 10
	s_add_i32 s4, 0, 0x18000
	v_lshl_add_u64 v[4:5], s[6:7], 0, v[4:5]
	v_and_b32_e32 v2, 0x70, v2
	s_add_i32 s3, s4, s35
	s_add_i32 s5, s2, 8
	v_lshl_add_u64 v[4:5], v[4:5], 0, v[2:3]
	v_writelane_b32 v253, s3, 4
	s_mov_b32 m0, s3
	s_bitset0_b32 m0, 16
	s_bitset1_b32 m0, 14
	s_lshl_b32 s3, s5, 3
	global_load_lds_dwordx4 v[4:5], off
	v_add_u32_e32 v4, s3, v6
	v_lshrrev_b32_e32 v2, 1, v4
	v_xor_b32_e32 v2, v2, v1
	v_ashrrev_i32_e32 v5, 31, v4
	v_lshlrev_b64 v[4:5], 7, v[4:5]
	v_lshlrev_b32_e32 v2, 4, v2
	s_lshl_b32 s10, s5, 10
	v_lshl_add_u64 v[4:5], s[6:7], 0, v[4:5]
	v_and_b32_e32 v2, 0x70, v2
	s_add_i32 s4, s4, s10
	v_lshl_add_u64 v[4:5], v[4:5], 0, v[2:3]
	s_mov_b32 m0, s4
	s_bitset0_b32 m0, 16
	s_bitset1_b32 m0, 14
	v_ashrrev_i32_e32 v6, 4, v1
	s_lshl_b32 s12, s2, 2
	v_writelane_b32 v253, s4, 1
	global_load_lds_dwordx4 v[4:5], off
	v_add_u32_e32 v4, s12, v6
	v_xor_b32_e32 v2, v4, v1
	v_ashrrev_i32_e32 v5, 31, v4
	v_readlane_b32 s6, v253, 32
	v_lshlrev_b64 v[4:5], 15, v[4:5]
	v_readlane_b32 s7, v253, 33
	v_lshlrev_b32_e32 v2, 4, v2
	s_add_i32 s4, 0, 0x1c000
	v_lshl_add_u64 v[4:5], s[6:7], 0, v[4:5]
	v_and_b32_e32 v2, 0xf0, v2
	s_add_i32 s8, s4, s35
	v_lshl_add_u64 v[4:5], v[4:5], 0, v[2:3]
	s_mov_b32 m0, s8
	s_lshl_b32 s14, s5, 2
	global_load_lds_dwordx4 v[4:5], off
	v_add_u32_e32 v4, s14, v6
	v_xor_b32_e32 v1, v4, v1
	v_ashrrev_i32_e32 v5, 31, v4
	v_lshlrev_b64 v[4:5], 15, v[4:5]
	v_lshlrev_b32_e32 v1, 4, v1
	v_lshl_add_u64 v[4:5], s[6:7], 0, v[4:5]
	v_and_b32_e32 v2, 0xf0, v1
	s_add_i32 s4, s4, s10
	v_lshl_add_u64 v[4:5], v[4:5], 0, v[2:3]
	s_mov_b32 m0, s4
	v_mov_b32_e32 v1, v63
	global_load_lds_dwordx4 v[4:5], off
	v_writelane_b32 v253, s8, 13
	v_ashrrev_i32_e32 v6, 3, v1
	v_add_u32_e32 v4, s0, v6
	v_writelane_b32 v253, s4, 2
	v_lshrrev_b32_e32 v2, 1, v4
	v_xor_b32_e32 v2, v2, v1
	v_ashrrev_i32_e32 v5, 31, v4
	v_readlane_b32 s4, v253, 54
	v_lshlrev_b64 v[4:5], 7, v[4:5]
	v_readlane_b32 s5, v253, 55
	v_lshlrev_b32_e32 v2, 4, v2
	v_and_b32_e32 v2, 0x70, v2
	v_lshl_add_u64 v[4:5], s[4:5], 0, v[4:5]
	s_add_i32 s16, s35, 0
	v_lshl_add_u64 v[4:5], v[4:5], 0, v[2:3]
	s_mov_b32 m0, s16
	s_add_i32 s17, s10, 0
	global_load_lds_dwordx4 v[4:5], off
	v_add_u32_e32 v4, s3, v6
	v_lshrrev_b32_e32 v2, 1, v4
	v_xor_b32_e32 v2, v2, v1
	v_ashrrev_i32_e32 v5, 31, v4
	v_lshlrev_b64 v[4:5], 7, v[4:5]
	v_lshlrev_b32_e32 v2, 4, v2
	v_lshl_add_u64 v[4:5], s[4:5], 0, v[4:5]
	v_and_b32_e32 v2, 0x70, v2
	v_lshl_add_u64 v[4:5], v[4:5], 0, v[2:3]
	s_mov_b32 m0, s17
	v_ashrrev_i32_e32 v6, 4, v1
	global_load_lds_dwordx4 v[4:5], off
	v_add_u32_e32 v4, s12, v6
	v_xor_b32_e32 v2, v4, v1
	v_ashrrev_i32_e32 v5, 31, v4
	v_readlane_b32 s4, v253, 37
	v_lshlrev_b64 v[4:5], 15, v[4:5]
	v_readlane_b32 s5, v253, 38
	v_lshlrev_b32_e32 v2, 4, v2
	v_and_b32_e32 v2, 0xf0, v2
	v_lshl_add_u64 v[4:5], s[4:5], 0, v[4:5]
	s_add_i32 s6, s16, 0x4000
	v_lshl_add_u64 v[4:5], v[4:5], 0, v[2:3]
	s_mov_b32 m0, s6
	s_bitset0_b32 m0, 14
	s_bitset1_b32 m0, 16
	v_writelane_b32 v254, s6, 58
	global_load_lds_dwordx4 v[4:5], off
	v_add_u32_e32 v4, s14, v6
	v_ashrrev_i32_e32 v5, 31, v4
	v_xor_b32_e32 v1, v4, v1
	v_lshlrev_b64 v[4:5], 15, v[4:5]
	v_lshl_add_u64 v[4:5], s[4:5], 0, v[4:5]
	s_add_i32 s4, s17, 0x4000
	v_and_b32_e32 v64, 15, v0
	v_lshlrev_b32_e32 v1, 4, v1
	v_writelane_b32 v254, s4, 59
	s_mov_b32 m0, s4
	s_bitset0_b32 m0, 14
	s_bitset1_b32 m0, 16
	v_readlane_b32 s4, v253, 56
	v_and_b32_e32 v2, 0xf0, v1
	s_lshl_b32 s87, s2, 4
	v_or_b32_e32 v1, s4, v64
	v_add_u32_e32 v28, s87, v1
	v_lshl_add_u64 v[4:5], v[4:5], 0, v[2:3]
	v_ashrrev_i32_e32 v29, 31, v28
	v_readlane_b32 s4, v253, 8
	global_load_lds_dwordx4 v[4:5], off
	v_lshlrev_b64 v[4:5], 7, v[28:29]
	v_readlane_b32 s5, v253, 9
	v_and_b32_e32 v2, 48, v0
	s_cmp_gt_i32 s2, 3
	v_lshl_add_u64 v[4:5], s[4:5], 0, v[4:5]
	v_lshl_add_u64 v[4:5], v[4:5], 0, v[2:3]
	global_load_dwordx4 v[8:11], v[4:5], off
	s_nop 0
	global_load_dwordx4 v[4:7], v[4:5], off offset:64
	s_cbranch_scc1 .LBB0_767
	s_setprio 1

.LBB0_789:
	v_mov_b32_e32 v0, v170
	v_readlane_b32 s6, v253, 57
	v_readfirstlane_b32 s0, v0
	v_and_b32_e32 v4, 63, v0
	s_ashr_i32 s0, s0, 6
	v_mov_b32_e32 v5, v4
	s_lshl_b32 s1, s0, 3
	v_ashrrev_i32_e32 v6, 3, v5
	v_add_u32_e32 v0, s1, v6
	v_lshrrev_b32_e32 v1, 1, v0
	v_xor_b32_e32 v2, v1, v5
	v_ashrrev_i32_e32 v1, 31, v0
	v_lshlrev_b64 v[0:1], 7, v[0:1]
	v_readlane_b32 s7, v253, 58
	v_lshlrev_b32_e32 v2, 4, v2
	v_and_b32_e32 v2, 0x70, v2
	v_lshl_add_u64 v[0:1], s[6:7], 0, v[0:1]
	s_lshl_b32 s2, s0, 10
	s_add_i32 s82, 0, 0x18000
	s_add_i32 s3, s0, 8
	v_lshl_add_u64 v[0:1], v[0:1], 0, v[2:3]
	s_add_i32 m0, s82, s2
	s_bitset0_b32 m0, 16
	s_bitset1_b32 m0, 14
	s_lshl_b32 s4, s3, 3
	global_load_lds_dwordx4 v[0:1], off
	v_add_u32_e32 v0, s4, v6
	v_lshrrev_b32_e32 v1, 1, v0
	v_xor_b32_e32 v2, v1, v5
	v_ashrrev_i32_e32 v1, 31, v0
	v_lshlrev_b64 v[0:1], 7, v[0:1]
	v_lshlrev_b32_e32 v2, 4, v2
	v_lshl_add_u64 v[0:1], s[6:7], 0, v[0:1]
	v_and_b32_e32 v2, 0x70, v2
	s_lshl_b32 s5, s3, 10
	v_lshl_add_u64 v[0:1], v[0:1], 0, v[2:3]
	s_add_i32 m0, s82, s5
	s_bitset0_b32 m0, 16
	s_bitset1_b32 m0, 14
	v_ashrrev_i32_e32 v6, 4, v5
	s_lshl_b32 s0, s0, 2
	global_load_lds_dwordx4 v[0:1], off
	v_add_u32_e32 v0, s0, v6
	v_xor_b32_e32 v2, v0, v5
	v_ashrrev_i32_e32 v1, 31, v0
	v_readlane_b32 s8, v253, 59
	v_lshlrev_b64 v[0:1], 15, v[0:1]
	v_readlane_b32 s9, v253, 60
	v_lshlrev_b32_e32 v2, 4, v2
	v_and_b32_e32 v2, 0xf0, v2
	v_lshl_add_u64 v[0:1], s[8:9], 0, v[0:1]
	s_add_i32 s62, 0, 0x1c000
	v_lshl_add_u64 v[0:1], v[0:1], 0, v[2:3]
	s_add_i32 m0, s62, s2
	s_lshl_b32 s3, s3, 2
	global_load_lds_dwordx4 v[0:1], off
	v_add_u32_e32 v0, s3, v6
	v_xor_b32_e32 v2, v0, v5
	v_ashrrev_i32_e32 v1, 31, v0
	v_lshlrev_b64 v[0:1], 15, v[0:1]
	v_lshlrev_b32_e32 v2, 4, v2
	v_lshl_add_u64 v[0:1], s[8:9], 0, v[0:1]
	v_and_b32_e32 v2, 0xf0, v2
	v_lshl_add_u64 v[0:1], v[0:1], 0, v[2:3]
	s_add_i32 m0, s62, s5
	s_nop 0
	global_load_lds_dwordx4 v[0:1], off
	s_nop 0
	v_ashrrev_i32_e32 v5, 3, v4
	v_add_u32_e32 v0, s1, v5
	v_lshrrev_b32_e32 v1, 1, v0
	v_xor_b32_e32 v2, v1, v4
	v_ashrrev_i32_e32 v1, 31, v0
	v_lshlrev_b64 v[0:1], 7, v[0:1]
	v_lshlrev_b32_e32 v2, 4, v2
	v_lshl_add_u64 v[0:1], s[6:7], 0, v[0:1]
	v_and_b32_e32 v2, 0x70, v2
	s_add_i32 s1, s2, 0
	v_lshl_add_u64 v[0:1], v[0:1], 0, v[2:3]
	s_mov_b32 m0, s1
	s_add_i32 s2, s5, 0
	global_load_lds_dwordx4 v[0:1], off
	v_add_u32_e32 v0, s4, v5
	v_lshrrev_b32_e32 v1, 1, v0
	v_xor_b32_e32 v2, v1, v4
	v_ashrrev_i32_e32 v1, 31, v0
	v_lshlrev_b64 v[0:1], 7, v[0:1]
	v_lshlrev_b32_e32 v2, 4, v2
	v_lshl_add_u64 v[0:1], s[6:7], 0, v[0:1]
	v_and_b32_e32 v2, 0x70, v2
	v_lshl_add_u64 v[0:1], v[0:1], 0, v[2:3]
	s_mov_b32 m0, s2
	v_ashrrev_i32_e32 v5, 4, v4
	global_load_lds_dwordx4 v[0:1], off
	v_add_u32_e32 v0, s0, v5
	v_xor_b32_e32 v2, v0, v4
	v_ashrrev_i32_e32 v1, 31, v0
	v_lshlrev_b64 v[0:1], 15, v[0:1]
	v_lshlrev_b32_e32 v2, 4, v2
	v_lshl_add_u64 v[0:1], s[8:9], 0, v[0:1]
	v_and_b32_e32 v2, 0xf0, v2
	v_lshl_add_u64 v[0:1], v[0:1], 0, v[2:3]
	s_add_i32 m0, s1, 0x4000
	s_bitset0_b32 m0, 14
	s_bitset1_b32 m0, 16
	s_nop 0
	global_load_lds_dwordx4 v[0:1], off
	v_add_u32_e32 v0, s3, v5
	v_xor_b32_e32 v2, v0, v4
	v_ashrrev_i32_e32 v1, 31, v0
	v_lshlrev_b64 v[0:1], 15, v[0:1]
	v_lshlrev_b32_e32 v2, 4, v2
	v_lshl_add_u64 v[0:1], s[8:9], 0, v[0:1]
	v_and_b32_e32 v2, 0xf0, v2
	v_lshl_add_u64 v[0:1], v[0:1], 0, v[2:3]
	s_add_i32 m0, s2, 0x4000
	s_bitset0_b32 m0, 14
	s_bitset1_b32 m0, 16
	s_nop 0
	global_load_lds_dwordx4 v[0:1], off
	s_waitcnt vmcnt(0)
	s_waitcnt vmcnt(0) lgkmcnt(0)
	s_barrier
	s_mov_b64 s[4:5], exec
	v_readlane_b32 s0, v252, 2
	v_readlane_b32 s1, v252, 3
	s_and_b64 s[0:1], s[4:5], s[0:1]
	s_mov_b64 exec, s[0:1]
	s_cbranch_execz .LBB0_841
	v_mov_b32_e32 v0, 0x20000
	ds_read_b64 v[0:1], v0
	s_getreg_b32 s44, hwreg(HW_REG_XCC_ID, 0, 4)
	s_lshl_b32 s44, s44, 7
	s_add_u32 s44, s44, 0xdc03600
	v_mov_b32_e32 v2, s44
	v_mov_b32_e32 v4, 1
	s_waitcnt vmcnt(0) lgkmcnt(0)
	global_atomic_add v5, v2, v4, s[42:43] sc0
	buffer_inv sc1
	s_add_u32 s100, s100, 1
	v_readfirstlane_b32 s46, v0
	v_readfirstlane_b32 s47, v1
	v_mov_b32_e32 v2, 0xdc03e00
	s_nop 3
	s_mul_i32 s48, s46, s100
	s_mul_i32 s49, s47, s100
	s_waitcnt vmcnt(1)
	v_readfirstlane_b32 s50, v5
	s_nop 3
	s_add_u32 s50, s50, 1
	s_cmp_lg_u32 s50, s48
	s_cbranch_scc1 .Lxb6_poll
	buffer_wbl2 sc1
	s_waitcnt vmcnt(0)
	global_atomic_add v2, v4, s[42:43]

.LBB0_844:
	s_waitcnt vmcnt(0) lgkmcnt(0)
	s_mov_b32 s79, 0x3e38aa3b
	s_mov_b32 s77, 0xc000
	s_mov_b32 s78, 0xffffc000
	v_readlane_b32 s1, v253, 23
	v_readfirstlane_b32 s0, v170
	s_nop 3
	s_lshr_b32 s0, s0, 6
	s_and_b32 s74, s1, 7
	s_lshl_b32 s74, s74, 5
	s_lshr_b32 s75, s1, 3
	s_add_u32 s74, s74, s75
	s_lshl_b32 s74, s74, 3
	s_and_b32 s4, s74, 7
	s_lshr_b32 s75, s74, 3
	s_and_b32 s5, s75, 3
	s_lshr_b32 s75, s75, 2
	s_and_b32 s3, s75, 3
	s_lshr_b32 s2, s75, 2
	s_sub_u32 s6, 8, s0
	s_lshl_b32 s70, s0, 10
	s_lshl_b32 s74, s2, 21
	s_lshl_b32 s75, s3, 19
	s_add_u32 s74, s74, s75
	s_add_u32 s34, s40, s74
	s_addc_u32 s35, s41, 0
	s_add_u32 s30, s34, 0x2000000
	s_addc_u32 s31, s35, 0
	s_lshl_b32 s74, s2, 16
	s_lshl_b32 s75, s3, 14
	s_add_u32 s74, s74, s75
	s_add_u32 s74, s74, 0xc000000
	s_add_u32 s58, s42, s74
	s_addc_u32 s59, s43, 0
	s_add_u32 s74, s2, 16
	s_lshl_b32 s74, s74, 2
	s_add_u32 s74, s74, s3
	s_lshl_b32 s74, s74, 19
	s_add_u32 s60, s42, s74
	s_addc_u32 s61, s43, 0
	s_lshl_b32 s74, s2, 6
	s_add_u32 s74, s74, 1024
	s_lshl_b32 s74, s74, 15
	s_lshl_b32 s75, s3, 13
	s_add_u32 s74, s74, s75
	s_add_u32 s74, s74, 0x6000000
	s_add_u32 s64, s42, s74
	s_addc_u32 s65, s43, 0
	v_and_b32_e32 v141, 63, v170
	v_and_b32_e32 v241, 15, v141
	v_lshrrev_b32_e32 v242, 4, v141
	v_mov_b32_e32 v244, 0xf149f2ca
	v_mov_b32_e32 v248, 0
	v_mov_b32_e32 v249, 0
	v_lshrrev_b32_e32 v142, 1, v241
	v_xor_b32_e32 v142, v142, v242
	v_lshlrev_b32_e32 v142, 4, v142
	v_lshl_add_u32 v142, v241, 7, v142
	s_lshl_b32 s74, s0, 11
	v_add_u32_e32 v230, s74, v142
	v_xor_b32_e32 v231, 64, v230
	v_lshrrev_b32_e32 v142, 1, v242
	v_xor_b32_e32 v243, v142, v241
	v_and_b32_e32 v142, 1, v242
	v_lshlrev_b32_e32 v142, 3, v142
	v_lshl_add_u32 v142, v241, 8, v142
	v_add_u32_e32 v142, 0x10000, v142
	s_add_u32 s74, s0, 0
	s_and_b32 s75, s74, 7
	s_lshl_b32 s75, s75, 1
	s_lshr_b32 s74, s74, 3
	s_lshl_b32 s74, s74, 14
	v_xor_b32_e32 v143, s75, v243
	v_lshl_add_u32 v143, v143, 4, v142
	v_add_u32_e32 v221, s74, v143
	s_add_u32 s74, s0, 1
	s_and_b32 s75, s74, 7
	s_lshl_b32 s75, s75, 1
	s_lshr_b32 s74, s74, 3
	s_lshl_b32 s74, s74, 14
	v_xor_b32_e32 v143, s75, v243
	v_lshl_add_u32 v143, v143, 4, v142
	v_add_u32_e32 v222, s74, v143
	s_add_u32 s74, s0, 2
	s_and_b32 s75, s74, 7
	s_lshl_b32 s75, s75, 1
	s_lshr_b32 s74, s74, 3
	s_lshl_b32 s74, s74, 14
	v_xor_b32_e32 v143, s75, v243
	v_lshl_add_u32 v143, v143, 4, v142
	v_add_u32_e32 v223, s74, v143
	s_add_u32 s74, s0, 3
	s_and_b32 s75, s74, 7
	s_lshl_b32 s75, s75, 1
	s_lshr_b32 s74, s74, 3
	s_lshl_b32 s74, s74, 14
	v_xor_b32_e32 v143, s75, v243
	v_lshl_add_u32 v143, v143, 4, v142
	v_add_u32_e32 v224, s74, v143
	s_add_u32 s74, s0, 4
	s_and_b32 s75, s74, 7
	s_lshl_b32 s75, s75, 1
	s_lshr_b32 s74, s74, 3
	s_lshl_b32 s74, s74, 14
	v_xor_b32_e32 v143, s75, v243
	v_lshl_add_u32 v143, v143, 4, v142
	v_add_u32_e32 v225, s74, v143
	s_add_u32 s74, s0, 5
	s_and_b32 s75, s74, 7
	s_lshl_b32 s75, s75, 1
	s_lshr_b32 s74, s74, 3
	s_lshl_b32 s74, s74, 14
	v_xor_b32_e32 v143, s75, v243
	v_lshl_add_u32 v143, v143, 4, v142
	v_add_u32_e32 v226, s74, v143
	s_add_u32 s74, s0, 6
	s_and_b32 s75, s74, 7
	s_lshl_b32 s75, s75, 1
	s_lshr_b32 s74, s74, 3
	s_lshl_b32 s74, s74, 14
	v_xor_b32_e32 v143, s75, v243
	v_lshl_add_u32 v143, v143, 4, v142
	v_add_u32_e32 v227, s74, v143
	s_add_u32 s74, s0, 7
	s_and_b32 s75, s74, 7
	s_lshl_b32 s75, s75, 1
	s_lshr_b32 s74, s74, 3
	s_lshl_b32 s74, s74, 14
	v_xor_b32_e32 v143, s75, v243
	v_lshl_add_u32 v143, v143, 4, v142
	v_add_u32_e32 v228, s74, v143
	s_add_u32 s74, s0, 8
	s_and_b32 s75, s74, 7
	s_lshl_b32 s75, s75, 1
	s_lshr_b32 s74, s74, 3
	s_lshl_b32 s74, s74, 14
	v_xor_b32_e32 v143, s75, v243
	v_lshl_add_u32 v143, v143, 4, v142
	v_add_u32_e32 v229, s74, v143
	s_and_b32 s74, s0, 1
	s_lshl_b32 s74, s74, 2
	v_add_u32_e32 v142, s74, v242
	v_and_b32_e32 v143, 7, v141
	v_xor_b32_e32 v142, v142, v143
	v_lshlrev_b32_e32 v142, 4, v142
	v_lshrrev_b32_e32 v143, 3, v141
	s_lshl_b32 s74, s0, 3
	v_add_u32_e32 v143, s74, v143
	v_lshl_add_u32 v232, v143, 7, v142
	v_add_u32_e32 v233, 0x2000, v232
	s_and_b32 s74, s0, 3
	s_lshl_b32 s74, s74, 2
	v_add_u32_e32 v142, s74, v242
	v_xor_b32_e32 v142, v142, v241
	v_lshlrev_b32_e32 v142, 4, v142
	s_lshl_b32 s74, s0, 2
	v_add_u32_e32 v143, s74, v242
	v_lshl_add_u32 v234, v143, 15, v142
	v_add_u32_e32 v235, 0x100000, v234
	s_lshl_b32 s74, s0, 4
	v_add_u32_e32 v142, s74, v241
	v_lshlrev_b32_e32 v142, 2, v142
	v_lshlrev_b32_e32 v238, 2, v142
	v_lshlrev_b32_e32 v142, 7, v142
	v_lshl_add_u32 v236, v242, 4, v142
	v_lshl_add_u32 v237, v242, 3, v142
	v_xor_b32_e32 v142, 16, v141
	v_lshlrev_b32_e32 v239, 2, v142
	v_xor_b32_e32 v142, 32, v141
	v_lshlrev_b32_e32 v240, 2, v142
	s_add_u32 s74, s2, 17
	v_cvt_f32_u32_e32 v142, s74
	v_mul_f32_e32 v142, 0xc1000000, v142
	v_mul_f32_e32 v142, 0x3caaaaab, v142
	v_exp_f32_e32 v142, v142
	v_lshlrev_b32_e32 v144, 2, v242
	v_sub_u32_e32 v145, v241, v144
	v_mul_f32_e32 v142, 0x40800000, v142
	v_add_u32_e32 v145, 0x80, v145
	v_mul_f32_e32 v142, 0x3fb8aa3b, v142
	v_cvt_f32_i32_e32 v145, v145
	s_nop 0
	v_mul_f32_e64 v143, -v142, v145
	v_fmamk_f32 v185, v142, 0x0, v143
	v_fmamk_f32 v186, v142, 0x3f800000, v143
	v_fmamk_f32 v187, v142, 0x40000000, v143
	v_fmamk_f32 v188, v142, 0x40400000, v143
	v_fmamk_f32 v189, v142, 0x41800000, v143
	v_fmamk_f32 v190, v142, 0x41880000, v143
	v_fmamk_f32 v191, v142, 0x41900000, v143
	v_fmamk_f32 v192, v142, 0x41980000, v143
	v_fmamk_f32 v193, v142, 0x42000000, v143
	v_fmamk_f32 v194, v142, 0x42040000, v143
	v_fmamk_f32 v195, v142, 0x42080000, v143
	v_fmamk_f32 v196, v142, 0x420c0000, v143
	v_fmamk_f32 v197, v142, 0x42400000, v143
	v_fmamk_f32 v198, v142, 0x42440000, v143
	v_fmamk_f32 v199, v142, 0x42480000, v143
	v_fmamk_f32 v200, v142, 0x424c0000, v143
	v_fmamk_f32 v201, v142, 0x42800000, v143
	v_fmamk_f32 v202, v142, 0x42820000, v143
	v_fmamk_f32 v203, v142, 0x42840000, v143
	v_fmamk_f32 v204, v142, 0x42860000, v143
	v_fmamk_f32 v205, v142, 0x42a00000, v143
	v_fmamk_f32 v206, v142, 0x42a20000, v143
	v_fmamk_f32 v207, v142, 0x42a40000, v143
	v_fmamk_f32 v208, v142, 0x42a60000, v143
	v_fmamk_f32 v209, v142, 0x42c00000, v143
	v_fmamk_f32 v210, v142, 0x42c20000, v143
	v_fmamk_f32 v211, v142, 0x42c40000, v143
	v_fmamk_f32 v212, v142, 0x42c60000, v143
	v_fmamk_f32 v213, v142, 0x42e00000, v143
	v_fmamk_f32 v214, v142, 0x42e20000, v143
	v_fmamk_f32 v215, v142, 0x42e40000, v143
	v_fmamk_f32 v216, v142, 0x42e60000, v143
	v_fmamk_f32 v217, v142, 0x43000000, v143
	v_fmamk_f32 v218, v142, 0x43010000, v143
	v_fmamk_f32 v219, v142, 0x43020000, v143
	v_fmamk_f32 v220, v142, 0x43030000, v143
	v_add_u32_e32 v145, 0, v144
	v_cmp_lt_u32_e32 vcc, v145, v241
	s_nop 1
	v_cndmask_b32_e32 v185, v185, v244, vcc
	v_cmp_gt_u32_e32 vcc, v145, v241
	s_nop 1
	v_cndmask_b32_e32 v217, v217, v244, vcc
	v_add_u32_e32 v145, 1, v144
	v_cmp_lt_u32_e32 vcc, v145, v241
	s_nop 1
	v_cndmask_b32_e32 v186, v186, v244, vcc
	v_cmp_gt_u32_e32 vcc, v145, v241
	s_nop 1
	v_cndmask_b32_e32 v218, v218, v244, vcc
	v_add_u32_e32 v145, 2, v144
	v_cmp_lt_u32_e32 vcc, v145, v241
	s_nop 1
	v_cndmask_b32_e32 v187, v187, v244, vcc
	v_cmp_gt_u32_e32 vcc, v145, v241
	s_nop 1
	v_cndmask_b32_e32 v219, v219, v244, vcc
	v_add_u32_e32 v145, 3, v144
	v_cmp_lt_u32_e32 vcc, v145, v241
	s_nop 1
	v_cndmask_b32_e32 v188, v188, v244, vcc
	v_cmp_gt_u32_e32 vcc, v145, v241
	s_nop 1
	v_cndmask_b32_e32 v220, v220, v244, vcc
	s_lshl_b32 s74, s4, 9
	s_add_u32 s74, s74, s5
	s_lshl_b32 s75, s74, 7
	s_add_u32 s10, s30, s75
	s_addc_u32 s11, s31, 0
	s_add_u32 s86, s34, s75
	s_addc_u32 s87, s35, 0
	s_lshl_b32 s75, s74, 2
	s_add_u32 s88, s58, s75
	s_addc_u32 s89, s59, 0
	global_load_dwordx4 v[96:99], v236, s[10:11]
	global_load_dwordx4 v[100:103], v236, s[10:11] offset:64
	global_load_dwordx2 v[112:113], v237, s[86:87]
	global_load_dwordx2 v[114:115], v237, s[86:87] offset:32
	global_load_dwordx2 v[116:117], v237, s[86:87] offset:64
	global_load_dwordx2 v[118:119], v237, s[86:87] offset:96
	global_load_dword v120, v238, s[88:89]
	s_mov_b32 s7, 0

.LBB0_936:
	v_mov_b32_e32 v0, v170
	v_readlane_b32 s6, v254, 7
	v_readfirstlane_b32 s0, v0
	v_and_b32_e32 v4, 63, v0
	s_ashr_i32 s0, s0, 6
	v_mov_b32_e32 v5, v4
	s_lshl_b32 s1, s0, 3
	v_ashrrev_i32_e32 v6, 3, v5
	v_add_u32_e32 v0, s1, v6
	v_lshrrev_b32_e32 v1, 1, v0
	v_xor_b32_e32 v2, v1, v5
	v_ashrrev_i32_e32 v1, 31, v0
	v_lshlrev_b64 v[0:1], 7, v[0:1]
	v_readlane_b32 s7, v254, 8
	v_lshlrev_b32_e32 v2, 4, v2
	v_and_b32_e32 v2, 0x70, v2
	v_lshl_add_u64 v[0:1], s[6:7], 0, v[0:1]
	s_lshl_b32 s2, s0, 10
	s_add_i32 s3, s0, 8
	v_lshl_add_u64 v[0:1], v[0:1], 0, v[2:3]
	s_add_i32 m0, s82, s2
	s_bitset0_b32 m0, 16
	s_bitset1_b32 m0, 14
	s_lshl_b32 s4, s3, 3
	global_load_lds_dwordx4 v[0:1], off
	v_add_u32_e32 v0, s4, v6
	v_lshrrev_b32_e32 v1, 1, v0
	v_xor_b32_e32 v2, v1, v5
	v_ashrrev_i32_e32 v1, 31, v0
	v_lshlrev_b64 v[0:1], 7, v[0:1]
	v_lshlrev_b32_e32 v2, 4, v2
	v_lshl_add_u64 v[0:1], s[6:7], 0, v[0:1]
	v_and_b32_e32 v2, 0x70, v2
	s_lshl_b32 s5, s3, 10
	v_lshl_add_u64 v[0:1], v[0:1], 0, v[2:3]
	s_add_i32 m0, s82, s5
	s_bitset0_b32 m0, 16
	s_bitset1_b32 m0, 14
	v_ashrrev_i32_e32 v6, 4, v5
	s_lshl_b32 s0, s0, 2
	global_load_lds_dwordx4 v[0:1], off
	v_add_u32_e32 v0, s0, v6
	v_xor_b32_e32 v2, v0, v5
	v_ashrrev_i32_e32 v1, 31, v0
	v_readlane_b32 s12, v254, 13
	v_lshlrev_b64 v[0:1], 15, v[0:1]
	v_readlane_b32 s13, v254, 14
	v_lshlrev_b32_e32 v2, 4, v2
	v_and_b32_e32 v2, 0xf0, v2
	v_lshl_add_u64 v[0:1], s[12:13], 0, v[0:1]
	v_lshl_add_u64 v[0:1], v[0:1], 0, v[2:3]
	s_add_i32 m0, s62, s2
	s_lshl_b32 s3, s3, 2
	global_load_lds_dwordx4 v[0:1], off
	v_add_u32_e32 v0, s3, v6
	v_xor_b32_e32 v2, v0, v5
	v_ashrrev_i32_e32 v1, 31, v0
	v_lshlrev_b64 v[0:1], 15, v[0:1]
	v_lshlrev_b32_e32 v2, 4, v2
	v_lshl_add_u64 v[0:1], s[12:13], 0, v[0:1]
	v_and_b32_e32 v2, 0xf0, v2
	v_lshl_add_u64 v[0:1], v[0:1], 0, v[2:3]
	s_add_i32 m0, s62, s5
	s_nop 0
	global_load_lds_dwordx4 v[0:1], off
	s_nop 0
	v_ashrrev_i32_e32 v5, 3, v4
	v_add_u32_e32 v0, s1, v5
	v_lshrrev_b32_e32 v1, 1, v0
	v_xor_b32_e32 v2, v1, v4
	v_ashrrev_i32_e32 v1, 31, v0
	v_lshlrev_b64 v[0:1], 7, v[0:1]
	v_lshlrev_b32_e32 v2, 4, v2
	v_lshl_add_u64 v[0:1], s[6:7], 0, v[0:1]
	v_and_b32_e32 v2, 0x70, v2
	s_add_i32 s1, s2, 0
	v_lshl_add_u64 v[0:1], v[0:1], 0, v[2:3]
	s_mov_b32 m0, s1
	s_add_i32 s2, s5, 0
	global_load_lds_dwordx4 v[0:1], off
	v_add_u32_e32 v0, s4, v5
	v_lshrrev_b32_e32 v1, 1, v0
	v_xor_b32_e32 v2, v1, v4
	v_ashrrev_i32_e32 v1, 31, v0
	v_lshlrev_b64 v[0:1], 7, v[0:1]
	v_lshlrev_b32_e32 v2, 4, v2
	v_lshl_add_u64 v[0:1], s[6:7], 0, v[0:1]
	v_and_b32_e32 v2, 0x70, v2
	v_lshl_add_u64 v[0:1], v[0:1], 0, v[2:3]
	s_mov_b32 m0, s2
	v_ashrrev_i32_e32 v5, 4, v4
	global_load_lds_dwordx4 v[0:1], off
	v_add_u32_e32 v0, s0, v5
	v_xor_b32_e32 v2, v0, v4
	v_ashrrev_i32_e32 v1, 31, v0
	v_lshlrev_b64 v[0:1], 15, v[0:1]
	v_lshlrev_b32_e32 v2, 4, v2
	v_lshl_add_u64 v[0:1], s[12:13], 0, v[0:1]
	v_and_b32_e32 v2, 0xf0, v2
	v_lshl_add_u64 v[0:1], v[0:1], 0, v[2:3]
	s_add_i32 m0, s1, 0x4000
	s_bitset0_b32 m0, 14
	s_bitset1_b32 m0, 16
	s_nop 0
	global_load_lds_dwordx4 v[0:1], off
	v_add_u32_e32 v0, s3, v5
	v_xor_b32_e32 v2, v0, v4
	v_ashrrev_i32_e32 v1, 31, v0
	v_lshlrev_b64 v[0:1], 15, v[0:1]
	v_lshlrev_b32_e32 v2, 4, v2
	v_lshl_add_u64 v[0:1], s[12:13], 0, v[0:1]
	v_and_b32_e32 v2, 0xf0, v2
	v_lshl_add_u64 v[0:1], v[0:1], 0, v[2:3]
	s_add_i32 m0, s2, 0x4000
	s_bitset0_b32 m0, 14
	s_bitset1_b32 m0, 16
	s_nop 0
	global_load_lds_dwordx4 v[0:1], off
	s_waitcnt vmcnt(0)
	s_waitcnt vmcnt(0) lgkmcnt(0)
	s_barrier
	s_mov_b64 s[4:5], exec
	v_readlane_b32 s0, v252, 2
	v_readlane_b32 s1, v252, 3
	s_and_b64 s[0:1], s[4:5], s[0:1]
	s_mov_b64 exec, s[0:1]
	s_cbranch_execz .LBB0_988
	v_mov_b32_e32 v0, 0x20000
	ds_read_b64 v[0:1], v0
	s_getreg_b32 s44, hwreg(HW_REG_XCC_ID, 0, 4)
	s_lshl_b32 s44, s44, 7
	s_add_u32 s44, s44, 0xdc03600
	v_mov_b32_e32 v2, s44
	v_mov_b32_e32 v4, 1
	s_waitcnt vmcnt(0) lgkmcnt(0)
	global_atomic_add v5, v2, v4, s[42:43] sc0
	buffer_inv sc1
	s_add_u32 s100, s100, 1
	v_readfirstlane_b32 s46, v0
	v_readfirstlane_b32 s47, v1
	v_mov_b32_e32 v2, 0xdc03e00
	s_nop 3
	s_mul_i32 s48, s46, s100
	s_mul_i32 s49, s47, s100
	s_waitcnt vmcnt(1)
	v_readfirstlane_b32 s50, v5
	s_nop 3
	s_add_u32 s50, s50, 1
	s_cmp_lg_u32 s50, s48
	s_cbranch_scc1 .Lxb8_poll
	buffer_wbl2 sc1
	s_waitcnt vmcnt(0)
	global_atomic_add v2, v4, s[42:43]

.LBB0_991:
	s_waitcnt vmcnt(0) lgkmcnt(0)
	s_mov_b32 s79, 0x3e38aa3b
	s_mov_b32 s77, 0xc000
	s_mov_b32 s78, 0xffffc000
	v_readlane_b32 s1, v253, 23
	v_readfirstlane_b32 s0, v170
	s_nop 3
	s_lshr_b32 s0, s0, 6
	s_and_b32 s74, s1, 7
	s_lshl_b32 s74, s74, 5
	s_lshr_b32 s75, s1, 3
	s_add_u32 s74, s74, s75
	s_lshl_b32 s74, s74, 3
	s_and_b32 s4, s74, 1
	s_lshr_b32 s75, s74, 1
	s_and_b32 s5, s75, 15
	s_lshr_b32 s75, s75, 4
	s_and_b32 s3, s75, 3
	s_lshr_b32 s2, s75, 2
	s_sub_u32 s6, 8, s0
	s_lshl_b32 s70, s0, 10
	s_lshl_b32 s74, s2, 21
	s_lshl_b32 s75, s3, 19
	s_add_u32 s74, s74, s75
	s_add_u32 s34, s40, s74
	s_addc_u32 s35, s41, 0
	s_add_u32 s30, s34, 0x2000000
	s_addc_u32 s31, s35, 0
	s_lshl_b32 s74, s2, 16
	s_lshl_b32 s75, s3, 14
	s_add_u32 s74, s74, s75
	s_add_u32 s74, s74, 0xc000000
	s_add_u32 s58, s42, s74
	s_addc_u32 s59, s43, 0
	s_add_u32 s74, s2, 32
	s_lshl_b32 s74, s74, 2
	s_add_u32 s74, s74, s3
	s_lshl_b32 s74, s74, 19
	s_add_u32 s60, s42, s74
	s_addc_u32 s61, s43, 0
	s_lshl_b32 s74, s2, 6
	s_add_u32 s74, s74, 2048
	s_lshl_b32 s74, s74, 15
	s_lshl_b32 s75, s3, 13
	s_add_u32 s74, s74, s75
	s_add_u32 s74, s74, 0x6000000
	s_add_u32 s64, s42, s74
	s_addc_u32 s65, s43, 0
	v_and_b32_e32 v141, 63, v170
	v_and_b32_e32 v241, 15, v141
	v_lshrrev_b32_e32 v242, 4, v141
	v_mov_b32_e32 v244, 0xf149f2ca
	v_mov_b32_e32 v248, 0
	v_mov_b32_e32 v249, 0
	v_lshrrev_b32_e32 v142, 1, v241
	v_xor_b32_e32 v142, v142, v242
	v_lshlrev_b32_e32 v142, 4, v142
	v_lshl_add_u32 v142, v241, 7, v142
	s_lshl_b32 s74, s0, 11
	v_add_u32_e32 v230, s74, v142
	v_xor_b32_e32 v231, 64, v230
	v_lshrrev_b32_e32 v142, 1, v242
	v_xor_b32_e32 v243, v142, v241
	v_and_b32_e32 v142, 1, v242
	v_lshlrev_b32_e32 v142, 3, v142
	v_lshl_add_u32 v142, v241, 8, v142
	v_add_u32_e32 v142, 0x10000, v142
	s_add_u32 s74, s0, 0
	s_and_b32 s75, s74, 7
	s_lshl_b32 s75, s75, 1
	s_lshr_b32 s74, s74, 3
	s_lshl_b32 s74, s74, 14
	v_xor_b32_e32 v143, s75, v243
	v_lshl_add_u32 v143, v143, 4, v142
	v_add_u32_e32 v221, s74, v143
	s_add_u32 s74, s0, 1
	s_and_b32 s75, s74, 7
	s_lshl_b32 s75, s75, 1
	s_lshr_b32 s74, s74, 3
	s_lshl_b32 s74, s74, 14
	v_xor_b32_e32 v143, s75, v243
	v_lshl_add_u32 v143, v143, 4, v142
	v_add_u32_e32 v222, s74, v143
	s_add_u32 s74, s0, 2
	s_and_b32 s75, s74, 7
	s_lshl_b32 s75, s75, 1
	s_lshr_b32 s74, s74, 3
	s_lshl_b32 s74, s74, 14
	v_xor_b32_e32 v143, s75, v243
	v_lshl_add_u32 v143, v143, 4, v142
	v_add_u32_e32 v223, s74, v143
	s_add_u32 s74, s0, 3
	s_and_b32 s75, s74, 7
	s_lshl_b32 s75, s75, 1
	s_lshr_b32 s74, s74, 3
	s_lshl_b32 s74, s74, 14
	v_xor_b32_e32 v143, s75, v243
	v_lshl_add_u32 v143, v143, 4, v142
	v_add_u32_e32 v224, s74, v143
	s_add_u32 s74, s0, 4
	s_and_b32 s75, s74, 7
	s_lshl_b32 s75, s75, 1
	s_lshr_b32 s74, s74, 3
	s_lshl_b32 s74, s74, 14
	v_xor_b32_e32 v143, s75, v243
	v_lshl_add_u32 v143, v143, 4, v142
	v_add_u32_e32 v225, s74, v143
	s_add_u32 s74, s0, 5
	s_and_b32 s75, s74, 7
	s_lshl_b32 s75, s75, 1
	s_lshr_b32 s74, s74, 3
	s_lshl_b32 s74, s74, 14
	v_xor_b32_e32 v143, s75, v243
	v_lshl_add_u32 v143, v143, 4, v142
	v_add_u32_e32 v226, s74, v143
	s_add_u32 s74, s0, 6
	s_and_b32 s75, s74, 7
	s_lshl_b32 s75, s75, 1
	s_lshr_b32 s74, s74, 3
	s_lshl_b32 s74, s74, 14
	v_xor_b32_e32 v143, s75, v243
	v_lshl_add_u32 v143, v143, 4, v142
	v_add_u32_e32 v227, s74, v143
	s_add_u32 s74, s0, 7
	s_and_b32 s75, s74, 7
	s_lshl_b32 s75, s75, 1
	s_lshr_b32 s74, s74, 3
	s_lshl_b32 s74, s74, 14
	v_xor_b32_e32 v143, s75, v243
	v_lshl_add_u32 v143, v143, 4, v142
	v_add_u32_e32 v228, s74, v143
	s_add_u32 s74, s0, 8
	s_and_b32 s75, s74, 7
	s_lshl_b32 s75, s75, 1
	s_lshr_b32 s74, s74, 3
	s_lshl_b32 s74, s74, 14
	v_xor_b32_e32 v143, s75, v243
	v_lshl_add_u32 v143, v143, 4, v142
	v_add_u32_e32 v229, s74, v143
	s_and_b32 s74, s0, 1
	s_lshl_b32 s74, s74, 2
	v_add_u32_e32 v142, s74, v242
	v_and_b32_e32 v143, 7, v141
	v_xor_b32_e32 v142, v142, v143
	v_lshlrev_b32_e32 v142, 4, v142
	v_lshrrev_b32_e32 v143, 3, v141
	s_lshl_b32 s74, s0, 3
	v_add_u32_e32 v143, s74, v143
	v_lshl_add_u32 v232, v143, 7, v142
	v_add_u32_e32 v233, 0x2000, v232
	s_and_b32 s74, s0, 3
	s_lshl_b32 s74, s74, 2
	v_add_u32_e32 v142, s74, v242
	v_xor_b32_e32 v142, v142, v241
	v_lshlrev_b32_e32 v142, 4, v142
	s_lshl_b32 s74, s0, 2
	v_add_u32_e32 v143, s74, v242
	v_lshl_add_u32 v234, v143, 15, v142
	v_add_u32_e32 v235, 0x100000, v234
	s_lshl_b32 s74, s0, 4
	v_add_u32_e32 v142, s74, v241
	v_lshlrev_b32_e32 v142, 4, v142
	v_lshlrev_b32_e32 v238, 2, v142
	v_lshlrev_b32_e32 v142, 7, v142
	v_lshl_add_u32 v236, v242, 4, v142
	v_lshl_add_u32 v237, v242, 3, v142
	v_xor_b32_e32 v142, 16, v141
	v_lshlrev_b32_e32 v239, 2, v142
	v_xor_b32_e32 v142, 32, v141
	v_lshlrev_b32_e32 v240, 2, v142
	s_add_u32 s74, s2, 33
	v_cvt_f32_u32_e32 v142, s74
	v_mul_f32_e32 v142, 0xc1000000, v142
	v_mul_f32_e32 v142, 0x3caaaaab, v142
	v_exp_f32_e32 v142, v142
	v_lshlrev_b32_e32 v144, 2, v242
	v_sub_u32_e32 v145, v241, v144
	v_mul_f32_e32 v142, 0x41800000, v142
	v_add_u32_e32 v145, 0x80, v145
	v_mul_f32_e32 v142, 0x3fb8aa3b, v142
	v_cvt_f32_i32_e32 v145, v145
	s_nop 0
	v_mul_f32_e64 v143, -v142, v145
	v_fmamk_f32 v185, v142, 0x0, v143
	v_fmamk_f32 v186, v142, 0x3f800000, v143
	v_fmamk_f32 v187, v142, 0x40000000, v143
	v_fmamk_f32 v188, v142, 0x40400000, v143
	v_fmamk_f32 v189, v142, 0x41800000, v143
	v_fmamk_f32 v190, v142, 0x41880000, v143
	v_fmamk_f32 v191, v142, 0x41900000, v143
	v_fmamk_f32 v192, v142, 0x41980000, v143
	v_fmamk_f32 v193, v142, 0x42000000, v143
	v_fmamk_f32 v194, v142, 0x42040000, v143
	v_fmamk_f32 v195, v142, 0x42080000, v143
	v_fmamk_f32 v196, v142, 0x420c0000, v143
	v_fmamk_f32 v197, v142, 0x42400000, v143
	v_fmamk_f32 v198, v142, 0x42440000, v143
	v_fmamk_f32 v199, v142, 0x42480000, v143
	v_fmamk_f32 v200, v142, 0x424c0000, v143
	v_fmamk_f32 v201, v142, 0x42800000, v143
	v_fmamk_f32 v202, v142, 0x42820000, v143
	v_fmamk_f32 v203, v142, 0x42840000, v143
	v_fmamk_f32 v204, v142, 0x42860000, v143
	v_fmamk_f32 v205, v142, 0x42a00000, v143
	v_fmamk_f32 v206, v142, 0x42a20000, v143
	v_fmamk_f32 v207, v142, 0x42a40000, v143
	v_fmamk_f32 v208, v142, 0x42a60000, v143
	v_fmamk_f32 v209, v142, 0x42c00000, v143
	v_fmamk_f32 v210, v142, 0x42c20000, v143
	v_fmamk_f32 v211, v142, 0x42c40000, v143
	v_fmamk_f32 v212, v142, 0x42c60000, v143
	v_fmamk_f32 v213, v142, 0x42e00000, v143
	v_fmamk_f32 v214, v142, 0x42e20000, v143
	v_fmamk_f32 v215, v142, 0x42e40000, v143
	v_fmamk_f32 v216, v142, 0x42e60000, v143
	v_fmamk_f32 v217, v142, 0x43000000, v143
	v_fmamk_f32 v218, v142, 0x43010000, v143
	v_fmamk_f32 v219, v142, 0x43020000, v143
	v_fmamk_f32 v220, v142, 0x43030000, v143
	v_add_u32_e32 v145, 0, v144
	v_cmp_lt_u32_e32 vcc, v145, v241
	s_nop 1
	v_cndmask_b32_e32 v185, v185, v244, vcc
	v_cmp_gt_u32_e32 vcc, v145, v241
	s_nop 1
	v_cndmask_b32_e32 v217, v217, v244, vcc
	v_add_u32_e32 v145, 1, v144
	v_cmp_lt_u32_e32 vcc, v145, v241
	s_nop 1
	v_cndmask_b32_e32 v186, v186, v244, vcc
	v_cmp_gt_u32_e32 vcc, v145, v241
	s_nop 1
	v_cndmask_b32_e32 v218, v218, v244, vcc
	v_add_u32_e32 v145, 2, v144
	v_cmp_lt_u32_e32 vcc, v145, v241
	s_nop 1
	v_cndmask_b32_e32 v187, v187, v244, vcc
	v_cmp_gt_u32_e32 vcc, v145, v241
	s_nop 1
	v_cndmask_b32_e32 v219, v219, v244, vcc
	v_add_u32_e32 v145, 3, v144
	v_cmp_lt_u32_e32 vcc, v145, v241
	s_nop 1
	v_cndmask_b32_e32 v188, v188, v244, vcc
	v_cmp_gt_u32_e32 vcc, v145, v241
	s_nop 1
	v_cndmask_b32_e32 v220, v220, v244, vcc
	s_lshl_b32 s74, s4, 11
	s_add_u32 s74, s74, s5
	s_lshl_b32 s75, s74, 7
	s_add_u32 s10, s30, s75
	s_addc_u32 s11, s31, 0
	s_add_u32 s86, s34, s75
	s_addc_u32 s87, s35, 0
	s_lshl_b32 s75, s74, 2
	s_add_u32 s88, s58, s75
	s_addc_u32 s89, s59, 0
	global_load_dwordx4 v[96:99], v236, s[10:11]
	global_load_dwordx4 v[100:103], v236, s[10:11] offset:64
	global_load_dwordx2 v[112:113], v237, s[86:87]
	global_load_dwordx2 v[114:115], v237, s[86:87] offset:32
	global_load_dwordx2 v[116:117], v237, s[86:87] offset:64
	global_load_dwordx2 v[118:119], v237, s[86:87] offset:96
	global_load_dword v120, v238, s[88:89]
	s_mov_b32 s7, 0
